# chunk-end-state (E) stores write-through and scan E loads nt: the S5 chain's once-used f32 stream no longer pollutes the L2s that the projection team re-reads; on top of v66
# speedup vs baseline: 1.0198x; 1.0198x over previous
.LBB0_543:
	v_lshl_add_u32 v140, s10, 8, v1
	v_ashrrev_i32_e32 v141, 31, v140
	v_mad_i64_i32 v[142:143], s[22:23], s4, v149, v[140:141]
	v_lshlrev_b64 v[142:143], 10, v[142:143]
	v_lshl_add_u64 v[142:143], v[138:139], 0, v[142:143]
	global_store_dwordx4 v[142:143], v[34:37], off sc1
	global_store_dwordx4 v[142:143], v[38:41], off offset:64 sc1
	global_store_dwordx4 v[142:143], v[74:77], off offset:512 sc1
	global_store_dwordx4 v[142:143], v[78:81], off offset:576 sc1
	v_or_b32_e32 v34, 16, v140
	v_ashrrev_i32_e32 v35, 31, v34
	v_mad_i64_i32 v[34:35], s[22:23], s4, v149, v[34:35]
	v_lshlrev_b64 v[34:35], 10, v[34:35]
	v_lshl_add_u64 v[34:35], v[138:139], 0, v[34:35]
	global_store_dwordx4 v[34:35], v[18:21], off sc1
	global_store_dwordx4 v[34:35], v[22:25], off offset:64 sc1
	global_store_dwordx4 v[34:35], v[58:61], off offset:512 sc1
	global_store_dwordx4 v[34:35], v[62:65], off offset:576 sc1
	v_or_b32_e32 v18, 32, v140
	v_ashrrev_i32_e32 v19, 31, v18
	v_mad_i64_i32 v[18:19], s[22:23], s4, v149, v[18:19]
	v_lshlrev_b64 v[18:19], 10, v[18:19]
	v_lshl_add_u64 v[18:19], v[138:139], 0, v[18:19]
	global_store_dwordx4 v[18:19], v[10:13], off sc1
	global_store_dwordx4 v[18:19], v[14:17], off offset:64 sc1
	global_store_dwordx4 v[18:19], v[42:45], off offset:512 sc1
	global_store_dwordx4 v[18:19], v[46:49], off offset:576 sc1
	v_or_b32_e32 v10, 48, v140
	v_ashrrev_i32_e32 v11, 31, v10
	v_mad_i64_i32 v[10:11], s[22:23], s4, v149, v[10:11]
	v_lshlrev_b64 v[10:11], 10, v[10:11]
	v_lshl_add_u64 v[10:11], v[138:139], 0, v[10:11]
	global_store_dwordx4 v[10:11], v[2:5], off sc1
	global_store_dwordx4 v[10:11], v[6:9], off offset:64 sc1
	global_store_dwordx4 v[10:11], v[26:29], off offset:512 sc1
	global_store_dwordx4 v[10:11], v[30:33], off offset:576 sc1
	v_add_u32_e32 v2, 0x80, v140
	v_ashrrev_i32_e32 v3, 31, v2
	v_mad_i64_i32 v[2:3], s[22:23], s4, v149, v[2:3]
	v_lshlrev_b64 v[2:3], 10, v[2:3]
	v_lshl_add_u64 v[2:3], v[138:139], 0, v[2:3]
	global_store_dwordx4 v[2:3], v[98:101], off sc1
	global_store_dwordx4 v[2:3], v[102:105], off offset:64 sc1
	global_store_dwordx4 v[2:3], v[122:125], off offset:512 sc1
	global_store_dwordx4 v[2:3], v[126:129], off offset:576 sc1
	v_add_u32_e32 v2, 0x90, v140
	v_ashrrev_i32_e32 v3, 31, v2
	v_mad_i64_i32 v[2:3], s[22:23], s4, v149, v[2:3]
	v_lshlrev_b64 v[2:3], 10, v[2:3]
	v_lshl_add_u64 v[2:3], v[138:139], 0, v[2:3]
	global_store_dwordx4 v[2:3], v[82:85], off sc1
	global_store_dwordx4 v[2:3], v[86:89], off offset:64 sc1
	global_store_dwordx4 v[2:3], v[114:117], off offset:512 sc1
	global_store_dwordx4 v[2:3], v[118:121], off offset:576 sc1
	v_add_u32_e32 v2, 0xa0, v140
	v_ashrrev_i32_e32 v3, 31, v2
	v_mad_i64_i32 v[2:3], s[22:23], s4, v149, v[2:3]
	v_lshlrev_b64 v[2:3], 10, v[2:3]
	v_lshl_add_u64 v[2:3], v[138:139], 0, v[2:3]
	global_store_dwordx4 v[2:3], v[66:69], off sc1
	global_store_dwordx4 v[2:3], v[70:73], off offset:64 sc1
	global_store_dwordx4 v[2:3], v[106:109], off offset:512 sc1
	global_store_dwordx4 v[2:3], v[110:113], off offset:576 sc1
	v_add_u32_e32 v2, 0xb0, v140
	v_ashrrev_i32_e32 v3, 31, v2
	v_mad_i64_i32 v[2:3], s[4:5], s4, v149, v[2:3]
	v_lshlrev_b64 v[2:3], 10, v[2:3]
	v_lshl_add_u64 v[2:3], v[138:139], 0, v[2:3]
	s_and_b64 vcc, exec, s[40:41]
	s_mov_b64 s[4:5], -1
	global_store_dwordx4 v[2:3], v[50:53], off sc1
	global_store_dwordx4 v[2:3], v[54:57], off offset:64 sc1
	global_store_dwordx4 v[2:3], v[90:93], off offset:512 sc1
	global_store_dwordx4 v[2:3], v[94:97], off offset:576 sc1
	s_cbranch_vccnz .LBB0_536
	s_andn2_b64 vcc, exec, s[6:7]
	s_cbranch_vccnz .LBB0_535
	s_barrier
	s_branch .LBB0_535

.LBB0_593:
	s_bfe_u32 s29, s28, 0x10005
	s_and_b32 s16, s28, 31
	s_lshl_b32 s17, s16, 7
	s_lshl_b32 s18, s29, 6
	s_ashr_i32 s31, s28, 6
	s_bfe_i32 s21, s28, 0x10005
	s_or_b32 s17, s18, s17
	s_mul_i32 s30, s16, 0x140000
	s_add_u32 s16, s6, s30
	v_or_b32_e32 v3, s17, v2
	s_addc_u32 s17, s7, 0
	s_lshl_b32 s18, s29, 9
	s_add_u32 s16, s16, s18
	s_addc_u32 s17, s17, 0
	s_lshl_b32 s34, s31, 9
	s_cmp_eq_u32 s29, 0
	s_cselect_b64 s[18:19], -1, 0
	v_lshl_add_u64 v[136:137], s[16:17], 0, v[6:7]
	s_and_b64 s[16:17], s[18:19], exec
	s_cselect_b32 s16, s22, s23
	s_cselect_b32 s20, s27, 0xfffffc00
	s_add_i32 s16, s16, s34
	s_ashr_i32 s17, s16, 31
	s_lshl_b64 s[16:17], s[16:17], 10
	v_lshl_add_u64 v[10:11], v[136:137], 0, s[16:17]
	v_lshl_add_u64 v[12:13], v[10:11], 0, s[20:21]
	v_lshl_add_u64 v[14:15], v[12:13], 0, s[20:21]
	v_lshlrev_b32_e32 v3, 3, v3
	v_lshl_add_u64 v[16:17], v[14:15], 0, s[20:21]
	global_load_dwordx2 v[8:9], v3, s[8:9]
	global_load_dword v134, v[10:11], off nt
	global_load_dword v135, v[10:11], off offset:256 nt
	global_load_dword v132, v[12:13], off nt
	global_load_dword v133, v[12:13], off offset:256 nt
	global_load_dword v130, v[14:15], off nt
	global_load_dword v131, v[14:15], off offset:256 nt
	global_load_dword v128, v[16:17], off nt
	global_load_dword v129, v[16:17], off offset:256 nt
	v_lshl_add_u64 v[10:11], v[16:17], 0, s[20:21]
	v_lshl_add_u64 v[12:13], v[10:11], 0, s[20:21]
	v_lshl_add_u64 v[14:15], v[12:13], 0, s[20:21]
	v_lshl_add_u64 v[16:17], v[14:15], 0, s[20:21]
	global_load_dword v126, v[10:11], off nt
	global_load_dword v127, v[10:11], off offset:256 nt
	global_load_dword v124, v[12:13], off nt
	global_load_dword v125, v[12:13], off offset:256 nt
	global_load_dword v122, v[14:15], off nt
	global_load_dword v123, v[14:15], off offset:256 nt
	global_load_dword v120, v[16:17], off nt
	global_load_dword v121, v[16:17], off offset:256 nt
	v_lshl_add_u64 v[10:11], v[16:17], 0, s[20:21]
	v_lshl_add_u64 v[12:13], v[10:11], 0, s[20:21]
	v_lshl_add_u64 v[14:15], v[12:13], 0, s[20:21]
	v_lshl_add_u64 v[16:17], v[14:15], 0, s[20:21]
	global_load_dword v118, v[10:11], off nt
	global_load_dword v119, v[10:11], off offset:256 nt
	global_load_dword v116, v[12:13], off nt
	global_load_dword v117, v[12:13], off offset:256 nt
	global_load_dword v114, v[14:15], off nt
	global_load_dword v115, v[14:15], off offset:256 nt
	global_load_dword v112, v[16:17], off nt
	global_load_dword v113, v[16:17], off offset:256 nt
	v_lshl_add_u64 v[10:11], v[16:17], 0, s[20:21]
	v_lshl_add_u64 v[12:13], v[10:11], 0, s[20:21]
	v_lshl_add_u64 v[14:15], v[12:13], 0, s[20:21]
	v_lshl_add_u64 v[16:17], v[14:15], 0, s[20:21]
	global_load_dword v110, v[10:11], off nt
	global_load_dword v111, v[10:11], off offset:256 nt
	global_load_dword v108, v[12:13], off nt
	global_load_dword v109, v[12:13], off offset:256 nt
	global_load_dword v106, v[14:15], off nt
	global_load_dword v107, v[14:15], off offset:256 nt
	global_load_dword v104, v[16:17], off nt
	global_load_dword v105, v[16:17], off offset:256 nt
	v_lshl_add_u64 v[10:11], v[16:17], 0, s[20:21]
	v_lshl_add_u64 v[12:13], v[10:11], 0, s[20:21]
	v_lshl_add_u64 v[14:15], v[12:13], 0, s[20:21]
	v_lshl_add_u64 v[16:17], v[14:15], 0, s[20:21]
	global_load_dword v102, v[10:11], off nt
	global_load_dword v103, v[10:11], off offset:256 nt
	global_load_dword v100, v[12:13], off nt
	global_load_dword v101, v[12:13], off offset:256 nt
	global_load_dword v98, v[14:15], off nt
	global_load_dword v99, v[14:15], off offset:256 nt
	global_load_dword v96, v[16:17], off nt
	global_load_dword v97, v[16:17], off offset:256 nt
	v_lshl_add_u64 v[10:11], v[16:17], 0, s[20:21]
	v_lshl_add_u64 v[12:13], v[10:11], 0, s[20:21]
	v_lshl_add_u64 v[14:15], v[12:13], 0, s[20:21]
	v_lshl_add_u64 v[16:17], v[14:15], 0, s[20:21]
	global_load_dword v94, v[10:11], off nt
	global_load_dword v95, v[10:11], off offset:256 nt
	global_load_dword v92, v[12:13], off nt
	global_load_dword v93, v[12:13], off offset:256 nt
	global_load_dword v90, v[14:15], off nt
	global_load_dword v91, v[14:15], off offset:256 nt
	global_load_dword v88, v[16:17], off nt
	global_load_dword v89, v[16:17], off offset:256 nt
	v_lshl_add_u64 v[10:11], v[16:17], 0, s[20:21]
	v_lshl_add_u64 v[12:13], v[10:11], 0, s[20:21]
	v_lshl_add_u64 v[14:15], v[12:13], 0, s[20:21]
	v_lshl_add_u64 v[16:17], v[14:15], 0, s[20:21]
	global_load_dword v86, v[10:11], off nt
	global_load_dword v87, v[10:11], off offset:256 nt
	global_load_dword v84, v[12:13], off nt
	global_load_dword v85, v[12:13], off offset:256 nt
	global_load_dword v82, v[14:15], off nt
	global_load_dword v83, v[14:15], off offset:256 nt
	global_load_dword v80, v[16:17], off nt
	global_load_dword v81, v[16:17], off offset:256 nt
	v_lshl_add_u64 v[10:11], v[16:17], 0, s[20:21]
	v_lshl_add_u64 v[12:13], v[10:11], 0, s[20:21]
	v_lshl_add_u64 v[14:15], v[12:13], 0, s[20:21]
	v_lshl_add_u64 v[16:17], v[14:15], 0, s[20:21]
	global_load_dword v78, v[10:11], off nt
	global_load_dword v79, v[10:11], off offset:256 nt
	global_load_dword v76, v[12:13], off nt
	global_load_dword v77, v[12:13], off offset:256 nt
	global_load_dword v74, v[14:15], off nt
	global_load_dword v75, v[14:15], off offset:256 nt
	global_load_dword v72, v[16:17], off nt
	global_load_dword v73, v[16:17], off offset:256 nt
	v_lshl_add_u64 v[10:11], v[16:17], 0, s[20:21]
	v_lshl_add_u64 v[12:13], v[10:11], 0, s[20:21]
	v_lshl_add_u64 v[14:15], v[12:13], 0, s[20:21]
	v_lshl_add_u64 v[16:17], v[14:15], 0, s[20:21]
	global_load_dword v70, v[10:11], off nt
	global_load_dword v71, v[10:11], off offset:256 nt
	global_load_dword v68, v[12:13], off nt
	global_load_dword v69, v[12:13], off offset:256 nt
	global_load_dword v66, v[14:15], off nt
	global_load_dword v67, v[14:15], off offset:256 nt
	global_load_dword v64, v[16:17], off nt
	global_load_dword v65, v[16:17], off offset:256 nt
	v_lshl_add_u64 v[10:11], v[16:17], 0, s[20:21]
	v_lshl_add_u64 v[12:13], v[10:11], 0, s[20:21]
	v_lshl_add_u64 v[14:15], v[12:13], 0, s[20:21]
	v_lshl_add_u64 v[16:17], v[14:15], 0, s[20:21]
	global_load_dword v62, v[10:11], off nt
	global_load_dword v63, v[10:11], off offset:256 nt
	global_load_dword v60, v[12:13], off nt
	global_load_dword v61, v[12:13], off offset:256 nt
	global_load_dword v58, v[14:15], off nt
	global_load_dword v59, v[14:15], off offset:256 nt
	global_load_dword v56, v[16:17], off nt
	global_load_dword v57, v[16:17], off offset:256 nt
	v_lshl_add_u64 v[10:11], v[16:17], 0, s[20:21]
	v_lshl_add_u64 v[12:13], v[10:11], 0, s[20:21]
	v_lshl_add_u64 v[14:15], v[12:13], 0, s[20:21]
	v_lshl_add_u64 v[16:17], v[14:15], 0, s[20:21]
	global_load_dword v54, v[10:11], off nt
	global_load_dword v55, v[10:11], off offset:256 nt
	global_load_dword v52, v[12:13], off nt
	global_load_dword v53, v[12:13], off offset:256 nt
	global_load_dword v50, v[14:15], off nt
	global_load_dword v51, v[14:15], off offset:256 nt
	global_load_dword v48, v[16:17], off nt
	global_load_dword v49, v[16:17], off offset:256 nt
	v_lshl_add_u64 v[10:11], v[16:17], 0, s[20:21]
	v_lshl_add_u64 v[12:13], v[10:11], 0, s[20:21]
	v_lshl_add_u64 v[14:15], v[12:13], 0, s[20:21]
	v_lshl_add_u64 v[16:17], v[14:15], 0, s[20:21]
	global_load_dword v46, v[10:11], off nt
	global_load_dword v47, v[10:11], off offset:256 nt
	global_load_dword v44, v[12:13], off nt
	global_load_dword v45, v[12:13], off offset:256 nt
	global_load_dword v42, v[14:15], off nt
	global_load_dword v43, v[14:15], off offset:256 nt
	global_load_dword v40, v[16:17], off nt
	global_load_dword v41, v[16:17], off offset:256 nt
	v_lshl_add_u64 v[10:11], v[16:17], 0, s[20:21]
	v_lshl_add_u64 v[12:13], v[10:11], 0, s[20:21]
	v_lshl_add_u64 v[14:15], v[12:13], 0, s[20:21]
	v_lshl_add_u64 v[16:17], v[14:15], 0, s[20:21]
	global_load_dword v38, v[10:11], off nt
	global_load_dword v39, v[10:11], off offset:256 nt
	global_load_dword v36, v[12:13], off nt
	global_load_dword v37, v[12:13], off offset:256 nt
	global_load_dword v34, v[14:15], off nt
	global_load_dword v35, v[14:15], off offset:256 nt
	global_load_dword v32, v[16:17], off nt
	global_load_dword v33, v[16:17], off offset:256 nt
	v_lshl_add_u64 v[10:11], v[16:17], 0, s[20:21]
	v_lshl_add_u64 v[12:13], v[10:11], 0, s[20:21]
	v_lshl_add_u64 v[14:15], v[12:13], 0, s[20:21]
	v_lshl_add_u64 v[16:17], v[14:15], 0, s[20:21]
	global_load_dword v30, v[10:11], off nt
	global_load_dword v31, v[10:11], off offset:256 nt
	global_load_dword v28, v[12:13], off nt
	global_load_dword v29, v[12:13], off offset:256 nt
	global_load_dword v26, v[14:15], off nt
	global_load_dword v27, v[14:15], off offset:256 nt
	global_load_dword v24, v[16:17], off nt
	global_load_dword v25, v[16:17], off offset:256 nt
	v_lshl_add_u64 v[10:11], v[16:17], 0, s[20:21]
	v_lshl_add_u64 v[12:13], v[10:11], 0, s[20:21]
	v_lshl_add_u64 v[14:15], v[12:13], 0, s[20:21]
	v_lshl_add_u64 v[138:139], v[14:15], 0, s[20:21]
	global_load_dword v22, v[10:11], off nt
	global_load_dword v23, v[10:11], off offset:256 nt
	global_load_dword v20, v[12:13], off nt
	global_load_dword v21, v[12:13], off offset:256 nt
	global_load_dword v18, v[14:15], off nt
	global_load_dword v19, v[14:15], off offset:256 nt
	global_load_dword v16, v[138:139], off nt
	global_load_dword v17, v[138:139], off offset:256 nt
	v_lshl_add_u64 v[10:11], v[138:139], 0, s[20:21]
	v_lshl_add_u64 v[138:139], v[10:11], 0, s[20:21]
	v_lshl_add_u64 v[140:141], v[138:139], 0, s[20:21]
	v_lshl_add_u64 v[142:143], v[140:141], 0, s[20:21]
	global_load_dword v14, v[10:11], off nt
	global_load_dword v15, v[10:11], off offset:256 nt
	global_load_dword v12, v[138:139], off nt
	global_load_dword v13, v[138:139], off offset:256 nt
	s_nop 0
	global_load_dword v10, v[140:141], off nt
	global_load_dword v11, v[140:141], off offset:256 nt
	global_load_dword v4, v[142:143], off nt
	global_load_dword v3, v[142:143], off offset:256 nt
	s_mov_b64 s[20:21], -1
	s_and_b64 vcc, exec, s[38:39]
	s_waitcnt vmcnt(62)
	v_pk_mul_f32 v[138:139], v[8:9], 0 op_sel_hi:[1,0]
	s_nop 0
	v_sub_f32_e32 v140, v138, v139
	v_add_f32_e32 v141, v138, v139
	s_cbranch_vccnz .LBB0_595
	v_sub_f32_e32 v143, v138, v139
	v_add_f32_e32 v142, v138, v139
	s_mov_b64 s[20:21], 0
.LBB0_595:
	s_andn2_b64 vcc, exec, s[20:21]
	s_cbranch_vccnz .LBB0_597
	s_lshl_b32 s21, s31, 4
	s_add_i32 s20, s21, 0x400
	s_and_b64 s[34:35], s[18:19], exec
	s_cselect_b32 s31, 0, 15
	s_or_b32 s34, s31, s20
	s_ashr_i32 s35, s34, 31
	s_lshl_b64 s[34:35], s[34:35], 10
	v_lshl_add_u64 v[138:139], v[136:137], 0, s[34:35]
	s_and_b64 s[34:35], s[18:19], exec
	s_cselect_b32 s31, 1, 14
	s_or_b32 s34, s31, s20
	s_ashr_i32 s35, s34, 31
	s_lshl_b64 s[34:35], s[34:35], 10
	global_load_dword v144, v[138:139], off nt
	global_load_dword v145, v[138:139], off offset:256 nt
	v_lshl_add_u64 v[138:139], v[136:137], 0, s[34:35]
	s_and_b64 s[34:35], s[18:19], exec
	s_cselect_b32 s31, 2, 13
	s_or_b32 s34, s31, s20
	s_ashr_i32 s35, s34, 31
	s_lshl_b64 s[34:35], s[34:35], 10
	global_load_dword v146, v[138:139], off nt
	global_load_dword v147, v[138:139], off offset:256 nt
	v_lshl_add_u64 v[138:139], v[136:137], 0, s[34:35]
	s_and_b64 s[34:35], s[18:19], exec
	s_cselect_b32 s31, 3, 12
	s_or_b32 s34, s31, s20
	s_ashr_i32 s35, s34, 31
	s_lshl_b64 s[34:35], s[34:35], 10
	global_load_dword v148, v[138:139], off nt
	global_load_dword v149, v[138:139], off offset:256 nt
	v_lshl_add_u64 v[138:139], v[136:137], 0, s[34:35]
	s_and_b64 s[34:35], s[18:19], exec
	s_cselect_b32 s31, 4, 11
	s_or_b32 s34, s31, s20
	s_ashr_i32 s35, s34, 31
	s_lshl_b64 s[34:35], s[34:35], 10
	global_load_dword v150, v[138:139], off nt
	global_load_dword v151, v[138:139], off offset:256 nt
	v_lshl_add_u64 v[138:139], v[136:137], 0, s[34:35]
	s_and_b64 s[34:35], s[18:19], exec
	s_cselect_b32 s31, 5, 10
	s_or_b32 s34, s31, s20
	s_ashr_i32 s35, s34, 31
	s_lshl_b64 s[34:35], s[34:35], 10
	global_load_dword v152, v[138:139], off nt
	global_load_dword v153, v[138:139], off offset:256 nt
	v_lshl_add_u64 v[138:139], v[136:137], 0, s[34:35]
	s_and_b64 s[34:35], s[18:19], exec
	s_cselect_b32 s31, 6, 9
	s_or_b32 s34, s31, s20
	s_ashr_i32 s35, s34, 31
	s_lshl_b64 s[34:35], s[34:35], 10
	s_or_b32 s31, s29, s20
	global_load_dword v154, v[138:139], off nt
	global_load_dword v155, v[138:139], off offset:256 nt
	v_lshl_add_u64 v[138:139], v[136:137], 0, s[34:35]
	s_add_i32 s34, s31, 7
	s_ashr_i32 s35, s34, 31
	s_lshl_b64 s[34:35], s[34:35], 10
	global_load_dword v156, v[138:139], off nt
	global_load_dword v157, v[138:139], off offset:256 nt
	v_lshl_add_u64 v[138:139], v[136:137], 0, s[34:35]
	s_sub_i32 s34, s21, s29
	s_ashr_i32 s35, s34, 31
	s_lshl_b64 s[34:35], s[34:35], 10
	global_load_dword v158, v[138:139], off nt
	global_load_dword v159, v[138:139], off offset:256 nt
	v_lshl_add_u64 v[138:139], v[136:137], 0, s[34:35]
	s_mov_b64 s[34:35], 0x102000
	v_lshl_add_u64 v[142:143], v[138:139], 0, s[34:35]
	s_mov_b32 s21, 0x102000
	s_and_b64 s[34:35], s[18:19], exec
	v_add_co_u32_e32 v138, vcc, s21, v138
	s_cselect_b32 s21, 9, 6
	s_or_b32 s34, s21, s20
	s_ashr_i32 s35, s34, 31
	v_addc_co_u32_e32 v139, vcc, 0, v139, vcc
	s_lshl_b64 s[34:35], s[34:35], 10
	global_load_dword v160, v[138:139], off nt
	s_nop 0
	global_load_dword v142, v[142:143], off offset:256 nt
	v_lshl_add_u64 v[138:139], v[136:137], 0, s[34:35]
	s_and_b64 s[34:35], s[18:19], exec
	s_cselect_b32 s21, 10, 5
	s_or_b32 s34, s21, s20
	s_ashr_i32 s35, s34, 31
	s_lshl_b64 s[34:35], s[34:35], 10
	global_load_dword v143, v[138:139], off nt
	global_load_dword v161, v[138:139], off offset:256 nt
	v_lshl_add_u64 v[138:139], v[136:137], 0, s[34:35]
	s_and_b64 s[34:35], s[18:19], exec
	s_cselect_b32 s21, 11, 4
	s_or_b32 s34, s21, s20
	s_ashr_i32 s35, s34, 31
	s_lshl_b64 s[34:35], s[34:35], 10
	global_load_dword v162, v[138:139], off nt
	global_load_dword v163, v[138:139], off offset:256 nt
	v_lshl_add_u64 v[138:139], v[136:137], 0, s[34:35]
	s_and_b64 s[34:35], s[18:19], exec
	s_cselect_b32 s21, 12, 3
	s_or_b32 s34, s21, s20
	s_ashr_i32 s35, s34, 31
	s_lshl_b64 s[34:35], s[34:35], 10
	global_load_dword v164, v[138:139], off nt
	global_load_dword v165, v[138:139], off offset:256 nt
	v_lshl_add_u64 v[138:139], v[136:137], 0, s[34:35]
	s_and_b64 s[34:35], s[18:19], exec
	s_cselect_b32 s21, 13, 2
	s_or_b32 s34, s21, s20
	s_ashr_i32 s35, s34, 31
	global_load_dword v166, v[138:139], off nt
	global_load_dword v167, v[138:139], off offset:256 nt
	s_lshl_b64 s[34:35], s[34:35], 10
	v_lshl_add_u64 v[138:139], v[136:137], 0, s[34:35]
	s_and_b64 s[34:35], s[18:19], exec
	s_cselect_b32 s21, 14, 1
	s_or_b32 s34, s21, s20
	global_load_dword v168, v[138:139], off nt
	global_load_dword v169, v[138:139], off offset:256 nt
	s_ashr_i32 s35, s34, 31
	s_lshl_b64 s[34:35], s[34:35], 10
	v_lshl_add_u64 v[138:139], v[136:137], 0, s[34:35]
	s_and_b64 s[34:35], s[18:19], exec
	s_cselect_b32 s21, 15, 0
	global_load_dword v170, v[138:139], off nt
	s_nop 0
	global_load_dword v138, v[138:139], off offset:256 nt
	s_or_b32 s20, s21, s20
	s_ashr_i32 s21, s20, 31
	s_lshl_b64 s[20:21], s[20:21], 10
	v_lshl_add_u64 v[136:137], v[136:137], 0, s[20:21]
	global_load_dword v139, v[136:137], off nt
	s_nop 0
	global_load_dword v136, v[136:137], off offset:256 nt
	s_waitcnt vmcnt(31)
	v_add_f32_e32 v137, v140, v144
	s_waitcnt vmcnt(30)
	v_add_f32_e32 v144, v141, v145
	v_mul_f32_e32 v145, v9, v144
	v_fma_f32 v145, v8, v137, -v145
	v_mul_f32_e32 v137, v9, v137
	v_fmac_f32_e32 v137, v8, v144
	s_waitcnt vmcnt(28)
	v_add_f32_e32 v137, v137, v147
	v_add_f32_e32 v145, v145, v146
	v_mul_f32_e32 v144, v9, v137
	v_fma_f32 v144, v8, v145, -v144
	v_mul_f32_e32 v145, v9, v145
	v_fmac_f32_e32 v145, v8, v137
	s_waitcnt vmcnt(26)
	v_add_f32_e32 v137, v145, v149
	v_add_f32_e32 v144, v144, v148
	v_mul_f32_e32 v145, v9, v137
	v_fma_f32 v145, v8, v144, -v145
	v_mul_f32_e32 v144, v9, v144
	v_fmac_f32_e32 v144, v8, v137
	s_waitcnt vmcnt(24)
	v_add_f32_e32 v137, v144, v151
	v_add_f32_e32 v145, v145, v150
	v_mul_f32_e32 v144, v9, v137
	v_fma_f32 v144, v8, v145, -v144
	v_mul_f32_e32 v145, v9, v145
	v_fmac_f32_e32 v145, v8, v137
	s_waitcnt vmcnt(22)
	v_add_f32_e32 v137, v145, v153
	v_add_f32_e32 v144, v144, v152
	v_mul_f32_e32 v145, v9, v137
	v_fma_f32 v145, v8, v144, -v145
	v_mul_f32_e32 v144, v9, v144
	v_fmac_f32_e32 v144, v8, v137
	s_waitcnt vmcnt(20)
	v_add_f32_e32 v137, v144, v155
	v_add_f32_e32 v145, v145, v154
	v_mul_f32_e32 v144, v9, v137
	v_fma_f32 v144, v8, v145, -v144
	v_mul_f32_e32 v145, v9, v145
	v_fmac_f32_e32 v145, v8, v137
	s_waitcnt vmcnt(18)
	v_add_f32_e32 v137, v145, v157
	v_add_f32_e32 v144, v144, v156
	v_mul_f32_e32 v145, v9, v137
	v_fma_f32 v145, v8, v144, -v145
	v_mul_f32_e32 v144, v9, v144
	v_fmac_f32_e32 v144, v8, v137
	s_waitcnt vmcnt(16)
	v_add_f32_e32 v137, v144, v159
	v_add_f32_e32 v145, v145, v158
	v_mul_f32_e32 v144, v9, v137
	v_fma_f32 v144, v8, v145, -v144
	v_mul_f32_e32 v145, v9, v145
	v_fmac_f32_e32 v145, v8, v137
	s_waitcnt vmcnt(14)
	v_add_f32_e32 v137, v145, v142
	v_add_f32_e32 v144, v144, v160
	v_mul_f32_e32 v142, v9, v137
	v_fma_f32 v142, v8, v144, -v142
	s_waitcnt vmcnt(13)
	v_add_f32_e32 v142, v142, v143
	v_mul_f32_e32 v143, v9, v144
	v_fmac_f32_e32 v143, v8, v137
	s_waitcnt vmcnt(12)
	v_add_f32_e32 v137, v143, v161
	v_mul_f32_e32 v143, v9, v137
	v_fma_f32 v143, v8, v142, -v143
	v_mul_f32_e32 v142, v9, v142
	v_fmac_f32_e32 v142, v8, v137
	s_waitcnt vmcnt(10)
	v_add_f32_e32 v137, v142, v163
	v_add_f32_e32 v143, v143, v162
	v_mul_f32_e32 v142, v9, v137
	v_fma_f32 v142, v8, v143, -v142
	v_mul_f32_e32 v143, v9, v143
	v_fmac_f32_e32 v143, v8, v137
	s_waitcnt vmcnt(8)
	v_add_f32_e32 v137, v143, v165
	v_add_f32_e32 v142, v142, v164
	v_mul_f32_e32 v143, v9, v137
	v_fma_f32 v143, v8, v142, -v143
	v_mul_f32_e32 v142, v9, v142
	v_fmac_f32_e32 v142, v8, v137
	s_waitcnt vmcnt(6)
	v_add_f32_e32 v137, v142, v167
	v_add_f32_e32 v143, v143, v166
	v_mul_f32_e32 v142, v9, v137
	v_fma_f32 v142, v8, v143, -v142
	v_mul_f32_e32 v143, v9, v143
	v_fmac_f32_e32 v143, v8, v137
	s_waitcnt vmcnt(4)
	v_add_f32_e32 v137, v143, v169
	v_add_f32_e32 v142, v142, v168
	v_mul_f32_e32 v143, v9, v137
	v_fma_f32 v143, v8, v142, -v143
	v_mul_f32_e32 v142, v9, v142
	v_fmac_f32_e32 v142, v8, v137
	s_waitcnt vmcnt(2)
	v_add_f32_e32 v137, v142, v138
	v_add_f32_e32 v143, v143, v170
	v_mul_f32_e32 v138, v9, v137
	v_fma_f32 v138, v8, v143, -v138
	s_waitcnt vmcnt(1)
	v_add_f32_e32 v138, v138, v139
	v_mul_f32_e32 v139, v9, v143
	v_fmac_f32_e32 v139, v8, v137
	s_waitcnt vmcnt(0)
	v_add_f32_e32 v136, v139, v136
	v_mov_b32_e32 v142, v141
	v_mov_b32_e32 v143, v140
	ds_write2st64_b32 v1, v138, v136 offset0:16 offset1:17
